# attention K tile LDS swizzle on row bits 1-3 (no 2-way bank conflict on K fragment reads) plus QK block LDS reads prefetched 5 MFMAs ahead
# speedup vs baseline: 1.0180x; 1.0180x over previous
.LBB0_698:
	s_or_b64 exec, exec, s[8:9]
	s_waitcnt lgkmcnt(0)
	s_barrier
	ds_read_b32 v1, v175
	s_movk_i32 s8, 0x47f
	s_waitcnt lgkmcnt(0)
	v_cmp_lt_i32_e32 vcc, s8, v1
	v_readfirstlane_b32 s90, v1
	s_mov_b64 s[8:9], -1
	s_cbranch_vccnz .LBB0_693
	s_cmpk_gt_i32 s90, 0x7f
	s_cbranch_scc0 .LBB0_732
	s_add_i32 s8, s90, 0xffffff80
	s_lshr_b32 s8, s8, 6
	v_mov_b32_e32 v80, v226
	s_sub_i32 s10, 15, s8
	s_lshl_b32 s8, s90, 9
	v_ashrrev_i32_e32 v42, 6, v80
	s_and_b32 s12, s8, 0x7000
	s_lshl_b32 s8, s10, 8
	v_lshlrev_b32_e32 v2, 5, v42
	s_or_b32 s60, s8, s12
	v_ashrrev_i32_e32 v3, 31, v2
	v_and_b32_e32 v166, 31, v80
	v_lshl_add_u64 v[168:169], v[2:3], 0, s[60:61]
	s_and_b32 s11, s90, 7
	v_or_b32_e32 v4, v168, v166
	v_mov_b64_e32 v[2:3], s[46:47]
	v_bfe_u32 v1, v80, 5, 1
	v_mad_i64_i32 v[2:3], s[8:9], v4, s77, v[2:3]
	s_mul_i32 s60, s11, 0x180
	v_lshl_add_u64 v[2:3], v[2:3], 0, s[60:61]
	v_lshlrev_b32_e32 v170, 4, v1
	v_mov_b32_e32 v171, v0
	s_lshl_b32 s92, s10, 2
	s_lshl_b32 s8, s12, 11
	v_lshl_add_u64 v[38:39], v[2:3], 0, v[170:171]
	s_add_u32 s9, s69, s8
	global_load_dwordx4 v[2:5], v[38:39], off offset:256
	global_load_dwordx4 v[6:9], v[38:39], off offset:288
	global_load_dwordx4 v[10:13], v[38:39], off offset:320
	global_load_dwordx4 v[14:17], v[38:39], off offset:352
	s_addc_u32 s10, s70, 0
	s_lshl_b32 s60, s11, 7
	s_lshl_b32 s11, s11, 8
	s_add_u32 s14, s9, s11
	s_addc_u32 s15, s10, 0
	s_add_u32 s8, s3, s8
	v_ashrrev_i32_e32 v172, 4, v80
	s_addc_u32 s9, s63, 0
	v_lshlrev_b32_e32 v43, 3, v80
	v_add_u32_e32 v40, 32, v172
	s_add_u32 s64, s8, s11
	v_and_b32_e32 v174, 0x78, v43
	v_ashrrev_i32_e32 v176, 3, v80
	s_addc_u32 s65, s9, 0
	v_ashrrev_i32_e32 v173, 31, v172
	v_ashrrev_i32_e32 v41, 31, v40
	s_lshl_b32 s8, s12, 7
	v_lshlrev_b32_e32 v44, 1, v174
	v_lshlrev_b64 v[52:53], 11, v[172:173]
	v_lshlrev_b64 v[26:27], 11, v[40:41]
	s_add_u32 s8, s67, s8
	v_ashrrev_i32_e32 v177, 31, v176
	v_lshlrev_b32_e32 v81, 4, v80
	v_or_b32_e32 v52, v52, v44
	v_or_b32_e32 v26, v26, v44
	s_addc_u32 s9, s68, 0
	v_lshlrev_b64 v[34:35], 7, v[176:177]
	v_and_b32_e32 v50, 0x70, v81
	v_lshl_add_u64 v[18:19], s[14:15], 0, v[52:53]
	v_lshl_add_u64 v[22:23], s[14:15], 0, v[26:27]
	v_lshl_add_u64 v[28:29], s[64:65], 0, v[52:53]
	v_lshl_add_u64 v[30:31], s[64:65], 0, v[26:27]
	v_lshl_add_u64 v[34:35], s[8:9], 0, v[34:35]
	v_mov_b32_e32 v51, v0
	global_load_dwordx4 v[18:21], v[18:19], off
	v_lshl_add_u64 v[54:55], v[34:35], 0, v[50:51]
	global_load_dwordx4 v[22:25], v[22:23], off
	s_nop 0
	global_load_dwordx4 v[26:29], v[28:29], off
	s_nop 0
	global_load_dwordx4 v[30:33], v[30:31], off
	s_nop 0
	global_load_dwordx4 v[34:37], v[54:55], off
	global_load_dwordx4 v[126:129], v[38:39], off
	global_load_dwordx4 v[122:125], v[38:39], off offset:32
	global_load_dwordx4 v[118:121], v[38:39], off offset:64
	global_load_dwordx4 v[114:117], v[38:39], off offset:96
	global_load_dwordx4 v[110:113], v[38:39], off offset:128
	global_load_dwordx4 v[106:109], v[38:39], off offset:160
	global_load_dwordx4 v[102:105], v[38:39], off offset:192
	global_load_dwordx4 v[98:101], v[38:39], off offset:224
	s_movk_i32 s10, 0x1200
	v_mul_lo_u32 v41, v42, s10
	v_mul_u32_u24_e32 v42, 0x90, v166
	v_add3_u32 v41, s79, v41, v42
	v_add_u32_e32 v183, v41, v170
	v_and_b32_e32 v45, 0xfffff0, v172
	s_movk_i32 s10, 0x70
	v_mul_u32_u24_e32 v64, 0x180, v166
	v_lshlrev_b32_e32 v185, 3, v166
	v_and_b32_e32 v185, 0x70, v185
	v_bitop3_b32 v42, v170, v64, v185 bitop3:0xde
	v_add_u32_e32 v185, 0, v42
	v_or_b32_e32 v56, 64, v170
	v_lshlrev_b32_e32 v188, 3, v166
	v_and_b32_e32 v188, 0x70, v188
	v_bitop3_b32 v60, v56, v64, v188 bitop3:0xde
	v_add_u32_e32 v188, 0, v60
	v_or_b32_e32 v65, 0x60, v170
	v_lshlrev_b32_e32 v187, 3, v166
	v_and_b32_e32 v187, 0x70, v187
	v_bitop3_b32 v68, v65, v64, v187 bitop3:0xde
	v_add_u32_e32 v187, 0, v68
	v_and_b32_e32 v82, 63, v80
	v_ashrrev_i32_e32 v184, 7, v80
	v_add_u32_e32 v193, s92, v184
	s_add_i32 s92, s92, 4
	s_mov_b32 s16, 0
	s_waitcnt vmcnt(16)
	ds_write_b128 v183, v[2:5]
	s_waitcnt vmcnt(15)
	ds_write_b128 v183, v[6:9] offset:32
	s_waitcnt vmcnt(14)
	ds_write_b128 v183, v[10:13] offset:64
	s_waitcnt vmcnt(13)
	ds_write_b128 v183, v[14:17] offset:96
	v_lshlrev_b32_e32 v2, 1, v172
	v_and_b32_e32 v6, 0xfffff0, v40
	v_lshlrev_b32_e32 v7, 1, v40
	v_and_or_b32 v2, v2, 8, v45
	v_and_or_b32 v6, v7, 8, v6
	v_lshrrev_b32_e32 v3, 1, v172
	v_lshrrev_b32_e32 v2, 1, v2
	v_bfe_u32 v4, v43, 5, 2
	v_and_b32_e32 v5, 3, v172
	v_lshrrev_b32_e32 v6, 1, v6
	v_or_b32_e32 v2, v2, v4
	v_and_or_b32 v3, v3, 4, v5
	v_or_b32_e32 v4, v6, v4
	v_lshlrev_b32_e32 v2, 9, v2
	v_lshlrev_b32_e32 v3, 6, v3
	v_and_b32_e32 v5, 48, v44
	v_lshlrev_b32_e32 v4, 9, v4
	v_or3_b32 v2, v2, v3, v5
	v_or3_b32 v3, v4, v3, v5
	v_add_u32_e32 v189, 0, v2
	v_add_u32_e32 v190, 0, v3
	v_mul_lo_u32 v2, v172, s78
	v_lshrrev_b32_e32 v4, 1, v80
	v_bitop3_b32 v3, v44, v4, s10 bitop3:0x78
	v_lshlrev_b32_e32 v4, 3, v176
	v_add3_u32 v191, v3, v2, 0
	v_mul_lo_u32 v2, v176, s78
	v_or_b32_e32 v3, 0x100, v50
	v_and_b32_e32 v4, 0x70, v4
	v_xad_u32 v2, v3, v4, v2
	v_add_u32_e32 v192, 0, v2
	s_waitcnt vmcnt(0)
	v_or_b32_e32 v10, 32, v170
	v_lshlrev_b32_e32 v186, 3, v166
	v_and_b32_e32 v186, 0x70, v186
	v_bitop3_b32 v14, v10, v64, v186 bitop3:0xde
	v_add_u32_e32 v186, 0, v14
	s_waitcnt vmcnt(12)
	ds_write_b128 v189, v[18:21]
	s_mov_b64 s[10:11], 0x20000
	s_waitcnt vmcnt(11)
	ds_write_b128 v190, v[22:25]
	s_waitcnt vmcnt(10)
	ds_write_b128 v191, v[26:29] offset:32768
	s_waitcnt vmcnt(9)
	ds_write_b128 v191, v[30:33] offset:45056
	s_waitcnt vmcnt(8)
	ds_write_b128 v192, v[34:37] offset:32768
	s_waitcnt lgkmcnt(0)
	s_barrier
	ds_read_b128 v[2:5], v185 offset:32768
	ds_read_b128 v[6:9], v185 offset:32896
	s_waitcnt vmcnt(7) lgkmcnt(1)
	v_mfma_f32_32x32x16_bf16 v[18:33], v[2:5], v[126:129], 0
	ds_read_b128 v[2:5], v185 offset:45056
	ds_read_b128 v[10:13], v185 offset:33024
	s_mov_b32 s17, s16
	s_mov_b32 s18, s16
	s_mov_b32 s19, s16
	s_mov_b32 s20, s16
	s_mov_b32 s21, s16
	s_waitcnt lgkmcnt(1)
	v_mfma_f32_32x32x16_bf16 v[34:49], v[2:5], v[126:129], 0
	ds_read_b128 v[2:5], v186 offset:32768
	ds_read_b128 v[14:17], v186 offset:32896
	ds_read_b128 v[56:59], v186 offset:33024
	s_mov_b32 s22, s16
	s_mov_b32 s23, s16
	s_mov_b32 s24, s16
	s_mov_b32 s25, s16
	s_mov_b32 s26, s16
	s_waitcnt vmcnt(6) lgkmcnt(2)
	v_mfma_f32_32x32x16_bf16 v[18:33], v[2:5], v[122:125], v[18:33]
	ds_read_b128 v[2:5], v186 offset:45056
	s_mov_b32 s27, s16
	s_mov_b32 s28, s16
	s_mov_b32 s29, s16
	s_mov_b32 s30, s16
	s_mov_b32 s31, s16
	v_add_u32_e32 v194, 0x3000, v191
	s_waitcnt lgkmcnt(0)
	v_mfma_f32_32x32x16_bf16 v[34:49], v[2:5], v[122:125], v[34:49]
	ds_read_b128 v[2:5], v188 offset:32768
	ds_read_b128 v[60:63], v188 offset:32896
	ds_read_b128 v[64:67], v188 offset:33024
	v_lshl_add_u64 v[178:179], s[8:9], 0, v[50:51]
	s_mov_b32 s91, 2
	v_add_u32_e32 v200, 1, v193
	v_cmp_gt_u32_e64 s[8:9], 32, v82
	v_add_u32_e32 v198, 0xe000, v185
	s_waitcnt vmcnt(5) lgkmcnt(2)
	v_mfma_f32_32x32x16_bf16 v[18:33], v[2:5], v[118:121], v[18:33]
	ds_read_b128 v[2:5], v188 offset:45056
	v_add_u32_e32 v196, 0xe000, v186
	v_add_u32_e32 v197, 0xe000, v188
	v_add_u32_e32 v195, 0xe000, v187
	v_mov_b32_e32 v173, 0
	s_waitcnt lgkmcnt(0)
	v_mfma_f32_32x32x16_bf16 v[34:49], v[2:5], v[118:121], v[34:49]
	ds_read_b128 v[2:5], v187 offset:32768
	ds_read_b128 v[68:71], v187 offset:32896
	s_waitcnt vmcnt(4) lgkmcnt(1)
	v_mfma_f32_32x32x16_bf16 v[18:33], v[2:5], v[114:117], v[18:33]
	ds_read_b128 v[2:5], v187 offset:45056
	ds_read_b128 v[72:75], v187 offset:33024
	s_waitcnt lgkmcnt(1)
	v_mfma_f32_32x32x16_bf16 v[34:49], v[2:5], v[114:117], v[34:49]
	s_waitcnt vmcnt(3)
	v_mfma_f32_32x32x16_bf16 v[18:33], v[6:9], v[110:113], v[18:33]
	ds_read_b128 v[2:5], v185 offset:45184
	ds_read_b128 v[6:9], v185 offset:45312
	s_waitcnt lgkmcnt(1)
	v_mfma_f32_32x32x16_bf16 v[34:49], v[2:5], v[110:113], v[34:49]
	s_waitcnt vmcnt(2)
	v_mfma_f32_32x32x16_bf16 v[18:33], v[14:17], v[106:109], v[18:33]
	ds_read_b128 v[2:5], v186 offset:45184
	ds_read_b128 v[14:17], v186 offset:45312
	s_waitcnt lgkmcnt(1)
	v_mfma_f32_32x32x16_bf16 v[34:49], v[2:5], v[106:109], v[34:49]
	s_waitcnt vmcnt(1)
	v_mfma_f32_32x32x16_bf16 v[18:33], v[60:63], v[102:105], v[18:33]
	ds_read_b128 v[2:5], v188 offset:45184
	ds_read_b128 v[60:63], v188 offset:45312
	s_waitcnt lgkmcnt(1)
	v_mfma_f32_32x32x16_bf16 v[34:49], v[2:5], v[102:105], v[34:49]
	s_waitcnt vmcnt(0)
	v_mfma_f32_32x32x16_bf16 v[18:33], v[68:71], v[98:101], v[18:33]
	ds_read_b128 v[2:5], v187 offset:45184
	ds_read_b128 v[68:71], v187 offset:45312
	s_waitcnt lgkmcnt(1)
	v_mfma_f32_32x32x16_bf16 v[34:49], v[2:5], v[98:101], v[34:49]
	ds_read_b128 v[2:5], v183
	ds_read_b128 v[76:79], v183 offset:32
	s_waitcnt lgkmcnt(1)
	v_mfma_f32_32x32x16_bf16 v[18:33], v[10:13], v[2:5], v[18:33]
	v_mfma_f32_32x32x16_bf16 v[34:49], v[6:9], v[2:5], v[34:49]
	v_and_b32_e32 v2, 0x3fffffc0, v80
	v_lshl_add_u32 v167, v2, 2, s76
	v_lshlrev_b32_e32 v6, 3, v82
	v_and_b32_e32 v2, 0xc0, v81
	v_and_or_b32 v7, v6, 24, v2
	ds_read_b128 v[2:5], v183 offset:64
	v_lshlrev_b32_e32 v8, 1, v80
	s_waitcnt lgkmcnt(1)
	v_mfma_f32_32x32x16_bf16 v[18:33], v[56:59], v[76:79], v[18:33]
	ds_read_b128 v[56:59], v183 offset:96
	v_and_b32_e32 v8, 32, v8
	v_and_b32_e32 v6, 0x100, v6
	v_lshl_add_u32 v171, v166, 2, v167
	v_mfma_f32_32x32x16_bf16 v[34:49], v[14:17], v[76:79], v[34:49]
	v_or3_b32 v76, v7, v8, v6
	v_add_u32_e32 v182, 0, v76
	v_add_u32_e32 v177, s81, v76
	s_waitcnt lgkmcnt(1)
	v_mfma_f32_32x32x16_bf16 v[18:33], v[64:67], v[2:5], v[18:33]
	v_lshl_add_u64 v[64:65], v[52:53], 0, s[10:11]
	s_mov_b64 s[10:11], 0x30000
	v_lshl_add_u64 v[52:53], v[52:53], 0, s[10:11]
	s_movk_i32 s10, 0x2000
	v_mfma_f32_32x32x16_bf16 v[34:49], v[60:63], v[2:5], v[34:49]
	v_lshl_add_u64 v[60:61], s[14:15], 0, v[52:53]
	v_lshl_add_u64 v[52:53], s[64:65], 0, v[52:53]
	v_mov_b64_e32 v[2:3], s[16:17]
	v_mov_b64_e32 v[16:17], s[30:31]
	v_mov_b64_e32 v[4:5], s[18:19]
	v_mov_b64_e32 v[6:7], s[20:21]
	v_mov_b64_e32 v[8:9], s[22:23]
	s_waitcnt lgkmcnt(0)
	v_mfma_f32_32x32x16_bf16 v[18:33], v[72:75], v[56:59], v[18:33]
	v_mov_b64_e32 v[10:11], s[24:25]
	v_mov_b64_e32 v[12:13], s[26:27]
	v_mov_b64_e32 v[14:15], s[28:29]
	v_mfma_f32_32x32x16_bf16 v[34:49], v[68:71], v[56:59], v[34:49]
	v_lshl_add_u64 v[56:57], s[14:15], 0, v[64:65]
	v_lshl_add_u64 v[64:65], s[64:65], 0, v[64:65]
	global_load_dwordx4 v[56:59], v[56:57], off
	s_nop 0
	global_load_dwordx4 v[60:63], v[60:61], off
	s_nop 0
	global_load_dwordx4 v[64:67], v[64:65], off
	s_nop 0
	global_load_dwordx4 v[68:71], v[52:53], off
	v_add_co_u32_e32 v52, vcc, s10, v54
	v_max_f32_e32 v72, v19, v19
	s_nop 0
	v_addc_co_u32_e32 v53, vcc, 0, v55, vcc
	global_load_dwordx4 v[52:55], v[52:53], off
	v_max_f32_e32 v73, v18, v18
	v_max_f32_e32 v72, v73, v72
	v_max3_f32 v72, v72, v20, v21
	v_max3_f32 v72, v72, v22, v23
	v_max3_f32 v72, v72, v24, v25
	v_max3_f32 v72, v72, v26, v27
	v_max3_f32 v72, v72, v28, v29
	v_max3_f32 v72, v72, v30, v31
	v_max3_f32 v72, v72, v32, v33
	v_max3_f32 v72, v72, v34, v35
	v_max3_f32 v72, v72, v36, v37
	v_max3_f32 v72, v72, v38, v39
	v_max3_f32 v72, v72, v40, v41
	v_max3_f32 v72, v72, v42, v43
	v_max3_f32 v72, v72, v44, v45
	v_max3_f32 v72, v72, v46, v47
	v_max3_f32 v72, v72, v48, v49
	v_mov_b32_e32 v73, v72
	s_nop 1
	v_permlane32_swap_b32_e32 v72, v73
	v_max_f32_e32 v73, v73, v73
	v_max_f32_e32 v72, v72, v72
	v_max_f32_e32 v72, v72, v73
	v_add_f32_e32 v73, 0x7149f2ca, v72
	v_max_f32_e32 v72, 0xf149f2ca, v72
	v_cmp_ge_f32_e32 vcc, s80, v73
	v_sub_f32_e32 v73, 0xf149f2ca, v72
	v_mul_f32_e32 v73, 0x3dd53b94, v73
	v_exp_f32_e32 v73, v73
	s_cmp_eq_u64 vcc, exec
	s_cselect_b64 vcc, -1, 0
	v_cndmask_b32_e32 v201, v72, v180, vcc
	v_mul_f32_e32 v72, 0xbdd53b94, v201
	v_cndmask_b32_e64 v199, v73, 1.0, vcc
	v_mov_b32_e32 v73, v72
	v_fmamk_f32 v18, v18, 0x3dd53b94, v72
	v_fmamk_f32 v19, v19, 0x3dd53b94, v72
	v_fmamk_f32 v20, v20, 0x3dd53b94, v72
	v_fmamk_f32 v21, v21, 0x3dd53b94, v72
	v_fmamk_f32 v22, v22, 0x3dd53b94, v72
	v_fmamk_f32 v23, v23, 0x3dd53b94, v72
	v_fmamk_f32 v24, v24, 0x3dd53b94, v72
	v_fmamk_f32 v25, v25, 0x3dd53b94, v72
	v_fmamk_f32 v26, v26, 0x3dd53b94, v72
	v_fmamk_f32 v27, v27, 0x3dd53b94, v72
	v_fmamk_f32 v28, v28, 0x3dd53b94, v72
	v_fmamk_f32 v29, v29, 0x3dd53b94, v72
	v_fmamk_f32 v30, v30, 0x3dd53b94, v72
	v_fmamk_f32 v31, v31, 0x3dd53b94, v72
	v_fmamk_f32 v32, v32, 0x3dd53b94, v72
	v_fmac_f32_e32 v73, 0x3dd53b94, v33
	v_exp_f32_e32 v146, v18
	v_exp_f32_e32 v147, v19
	v_exp_f32_e32 v148, v20
	v_exp_f32_e32 v149, v21
	v_exp_f32_e32 v154, v22
	v_exp_f32_e32 v160, v23
	v_exp_f32_e32 v161, v24
	v_exp_f32_e32 v162, v25
	v_exp_f32_e32 v151, v26
	v_exp_f32_e32 v152, v27
	v_exp_f32_e32 v153, v28
	v_exp_f32_e32 v155, v29
	v_exp_f32_e32 v156, v30
	v_exp_f32_e32 v157, v31
	v_exp_f32_e32 v158, v32
	v_exp_f32_e32 v159, v73
	s_waitcnt vmcnt(0)
	v_pk_fma_f32 v[140:141], v[48:49], s[62:63], v[72:73] op_sel_hi:[1,0,0]
	v_pk_fma_f32 v[142:143], v[46:47], s[62:63], v[72:73] op_sel_hi:[1,0,0]
	v_pk_fma_f32 v[144:145], v[44:45], s[62:63], v[72:73] op_sel_hi:[1,0,0]
	v_pk_fma_f32 v[130:131], v[42:43], s[62:63], v[72:73] op_sel_hi:[1,0,0]
	v_pk_fma_f32 v[132:133], v[40:41], s[62:63], v[72:73] op_sel_hi:[1,0,0]
	v_pk_fma_f32 v[134:135], v[38:39], s[62:63], v[72:73] op_sel_hi:[1,0,0]
	v_pk_fma_f32 v[136:137], v[36:37], s[62:63], v[72:73] op_sel_hi:[1,0,0]
	v_pk_fma_f32 v[138:139], v[34:35], s[62:63], v[72:73] op_sel_hi:[1,0,0]
	s_waitcnt vmcnt(4)
	ds_write_b128 v189, v[56:59] offset:16384
	s_waitcnt vmcnt(3)
	ds_write_b128 v190, v[60:63] offset:16384
	s_waitcnt vmcnt(2)
	ds_write_b128 v191, v[64:67] offset:57344
	s_waitcnt vmcnt(1)
	ds_write_b128 v194, v[68:71] offset:57344
	s_waitcnt vmcnt(0)
	ds_write_b128 v192, v[52:55] offset:57344
	v_mov_b64_e32 v[64:65], v[16:17]
	v_mov_b64_e32 v[48:49], v[16:17]
	v_mov_b64_e32 v[32:33], v[16:17]
	v_mov_b64_e32 v[62:63], v[14:15]
	v_mov_b64_e32 v[60:61], v[12:13]
	v_mov_b64_e32 v[58:59], v[10:11]
	v_mov_b64_e32 v[56:57], v[8:9]
	v_mov_b64_e32 v[54:55], v[6:7]
	v_mov_b64_e32 v[52:53], v[4:5]
	v_mov_b64_e32 v[50:51], v[2:3]
	v_mov_b64_e32 v[46:47], v[14:15]
	v_mov_b64_e32 v[44:45], v[12:13]
	v_mov_b64_e32 v[42:43], v[10:11]
	v_mov_b64_e32 v[40:41], v[8:9]
	v_mov_b64_e32 v[38:39], v[6:7]
	v_mov_b64_e32 v[36:37], v[4:5]
	v_mov_b64_e32 v[34:35], v[2:3]
	v_mov_b64_e32 v[30:31], v[14:15]
	v_mov_b64_e32 v[28:29], v[12:13]
	v_mov_b64_e32 v[26:27], v[10:11]
	v_mov_b64_e32 v[24:25], v[8:9]
	v_mov_b64_e32 v[22:23], v[6:7]
	v_mov_b64_e32 v[20:21], v[4:5]
	v_mov_b64_e32 v[18:19], v[2:3]
	s_waitcnt lgkmcnt(0)
	s_barrier
.LBB0_701:
	s_add_i32 s17, s91, -1
	v_cmp_le_i32_e64 s[10:11], s17, v193
	v_mov_b32_e32 v66, 0xf149f2ca
	v_mov_b32_e32 v67, 0xf149f2ca
	v_mov_b32_e32 v68, 0xf149f2ca
	v_mov_b32_e32 v69, 0xf149f2ca
	v_mov_b32_e32 v70, 0xf149f2ca
	v_mov_b32_e32 v71, 0xf149f2ca
	v_mov_b32_e32 v72, 0xf149f2ca
	v_mov_b32_e32 v73, 0xf149f2ca
	v_mov_b32_e32 v74, 0xf149f2ca
	v_mov_b32_e32 v75, 0xf149f2ca
	v_mov_b32_e32 v76, 0xf149f2ca
	v_mov_b32_e32 v77, 0xf149f2ca
	v_mov_b32_e32 v78, 0xf149f2ca
	v_mov_b32_e32 v79, 0xf149f2ca
	v_mov_b32_e32 v80, 0xf149f2ca
	v_mov_b32_e32 v81, 0xf149f2ca
	v_mov_b32_e32 v82, 0xf149f2ca
	v_mov_b32_e32 v83, 0xf149f2ca
	v_mov_b32_e32 v84, 0xf149f2ca
	v_mov_b32_e32 v85, 0xf149f2ca
	v_mov_b32_e32 v86, 0xf149f2ca
	v_mov_b32_e32 v87, 0xf149f2ca
	v_mov_b32_e32 v88, 0xf149f2ca
	v_mov_b32_e32 v89, 0xf149f2ca
	v_mov_b32_e32 v90, 0xf149f2ca
	v_mov_b32_e32 v91, 0xf149f2ca
	v_mov_b32_e32 v92, 0xf149f2ca
	v_mov_b32_e32 v93, 0xf149f2ca
	v_mov_b32_e32 v94, 0xf149f2ca
	v_mov_b32_e32 v95, 0xf149f2ca
	v_mov_b32_e32 v96, 0xf149f2ca
	v_mov_b32_e32 v97, 0xf149f2ca
	s_and_saveexec_b64 s[12:13], s[10:11]
	s_cbranch_execz .LBB0_703
	ds_read_b128 v[202:205], v185 offset:57344
	ds_read_b128 v[206:209], v198 offset:12288
	ds_read_b128 v[210:213], v186 offset:57344
	ds_read_b128 v[214:217], v196 offset:12288
	ds_read_b128 v[218:221], v188 offset:57344
	ds_read_b128 v[222:225], v197 offset:12288
	s_waitcnt lgkmcnt(5)
	v_mfma_f32_32x32x16_bf16 v[82:97], v[202:205], v[126:129], 0
	ds_read_b128 v[228:231], v187 offset:57344
	s_waitcnt lgkmcnt(5)
	v_mfma_f32_32x32x16_bf16 v[66:81], v[206:209], v[126:129], 0
	ds_read_b128 v[202:205], v195 offset:12288
	s_waitcnt lgkmcnt(5)
	v_mfma_f32_32x32x16_bf16 v[82:97], v[210:213], v[122:125], v[82:97]
	ds_read_b128 v[206:209], v185 offset:57472
	s_waitcnt lgkmcnt(5)
	v_mfma_f32_32x32x16_bf16 v[66:81], v[214:217], v[122:125], v[66:81]
	ds_read_b128 v[210:213], v198 offset:12416
	s_waitcnt lgkmcnt(5)
	v_mfma_f32_32x32x16_bf16 v[82:97], v[218:221], v[118:121], v[82:97]
	ds_read_b128 v[214:217], v186 offset:57472
	s_waitcnt lgkmcnt(5)
	v_mfma_f32_32x32x16_bf16 v[66:81], v[222:225], v[118:121], v[66:81]
	ds_read_b128 v[218:221], v196 offset:12416
	s_waitcnt lgkmcnt(5)
	v_mfma_f32_32x32x16_bf16 v[82:97], v[228:231], v[114:117], v[82:97]
	ds_read_b128 v[222:225], v188 offset:57472
	s_waitcnt lgkmcnt(5)
	v_mfma_f32_32x32x16_bf16 v[66:81], v[202:205], v[114:117], v[66:81]
	ds_read_b128 v[228:231], v197 offset:12416
	ds_read_b128 v[232:235], v183
	s_waitcnt lgkmcnt(6)
	v_mfma_f32_32x32x16_bf16 v[82:97], v[206:209], v[110:113], v[82:97]
	ds_read_b128 v[202:205], v187 offset:57472
	s_waitcnt lgkmcnt(6)
	v_mfma_f32_32x32x16_bf16 v[66:81], v[210:213], v[110:113], v[66:81]
	ds_read_b128 v[206:209], v195 offset:12416
	ds_read_b128 v[236:239], v183 offset:32
	s_waitcnt lgkmcnt(7)
	v_mfma_f32_32x32x16_bf16 v[82:97], v[214:217], v[106:109], v[82:97]
	ds_read_b128 v[210:213], v185 offset:57600
	s_waitcnt lgkmcnt(7)
	v_mfma_f32_32x32x16_bf16 v[66:81], v[218:221], v[106:109], v[66:81]
	ds_read_b128 v[214:217], v198 offset:12544
	ds_read_b128 v[240:243], v183 offset:64
	s_waitcnt lgkmcnt(8)
	v_mfma_f32_32x32x16_bf16 v[82:97], v[222:225], v[102:105], v[82:97]
	ds_read_b128 v[218:221], v186 offset:57600
	s_waitcnt lgkmcnt(8)
	v_mfma_f32_32x32x16_bf16 v[66:81], v[228:231], v[102:105], v[66:81]
	ds_read_b128 v[222:225], v196 offset:12544
	s_waitcnt lgkmcnt(7)
	v_mfma_f32_32x32x16_bf16 v[82:97], v[202:205], v[98:101], v[82:97]
	ds_read_b128 v[228:231], v188 offset:57600
	s_waitcnt lgkmcnt(7)
	v_mfma_f32_32x32x16_bf16 v[66:81], v[206:209], v[98:101], v[66:81]
	ds_read_b128 v[202:205], v197 offset:12544
	s_waitcnt lgkmcnt(6)
	v_mfma_f32_32x32x16_bf16 v[82:97], v[210:213], v[232:235], v[82:97]
	ds_read_b128 v[206:209], v187 offset:57600
	s_waitcnt lgkmcnt(6)
	v_mfma_f32_32x32x16_bf16 v[66:81], v[214:217], v[232:235], v[66:81]
	ds_read_b128 v[210:213], v195 offset:12544
	ds_read_b128 v[232:235], v183 offset:96
	s_waitcnt lgkmcnt(6)
	v_mfma_f32_32x32x16_bf16 v[82:97], v[218:221], v[236:239], v[82:97]
	s_waitcnt lgkmcnt(5)
	v_mfma_f32_32x32x16_bf16 v[66:81], v[222:225], v[236:239], v[66:81]
	s_waitcnt lgkmcnt(4)
	v_mfma_f32_32x32x16_bf16 v[82:97], v[228:231], v[240:243], v[82:97]
	s_waitcnt lgkmcnt(3)
	v_mfma_f32_32x32x16_bf16 v[66:81], v[202:205], v[240:243], v[66:81]
	s_waitcnt lgkmcnt(0)
	v_mfma_f32_32x32x16_bf16 v[82:97], v[206:209], v[232:235], v[82:97]
	s_waitcnt lgkmcnt(0)
	v_mfma_f32_32x32x16_bf16 v[66:81], v[210:213], v[232:235], v[66:81]

.LBB0_709:
	v_cndmask_b32_e64 v201, v146, v201, s[12:13]
	v_mul_f32_e32 v140, 0xbdd53b94, v201
	v_fmamk_f32 v82, v82, 0x3dd53b94, v140
	v_fmamk_f32 v83, v83, 0x3dd53b94, v140
	v_fmamk_f32 v84, v84, 0x3dd53b94, v140
	v_fmamk_f32 v85, v85, 0x3dd53b94, v140
	v_fmamk_f32 v86, v86, 0x3dd53b94, v140
	v_fmamk_f32 v87, v87, 0x3dd53b94, v140
	v_fmamk_f32 v88, v88, 0x3dd53b94, v140
	v_fmamk_f32 v89, v89, 0x3dd53b94, v140
	v_fmamk_f32 v90, v90, 0x3dd53b94, v140
	v_fmamk_f32 v91, v91, 0x3dd53b94, v140
	v_fmamk_f32 v92, v92, 0x3dd53b94, v140
	v_fmamk_f32 v93, v93, 0x3dd53b94, v140
	v_fmamk_f32 v94, v94, 0x3dd53b94, v140
	v_fmamk_f32 v95, v95, 0x3dd53b94, v140
	v_fmamk_f32 v96, v96, 0x3dd53b94, v140
	v_fmamk_f32 v97, v97, 0x3dd53b94, v140
	v_exp_f32_e32 v133, v82
	v_exp_f32_e32 v136, v83
	v_exp_f32_e32 v137, v84
	v_exp_f32_e32 v141, v85
	v_exp_f32_e32 v142, v86
	v_exp_f32_e32 v144, v87
	v_exp_f32_e32 v145, v88
	v_exp_f32_e32 v146, v89
	v_exp_f32_e32 v130, v90
	v_exp_f32_e32 v131, v91
	v_exp_f32_e32 v132, v92
	v_exp_f32_e32 v134, v93
	v_exp_f32_e32 v135, v94
	v_exp_f32_e32 v138, v95
	v_exp_f32_e32 v139, v96
	v_exp_f32_e32 v143, v97
	v_fmamk_f32 v147, v66, 0x3dd53b94, v140
	v_fmamk_f32 v148, v67, 0x3dd53b94, v140
	v_fmamk_f32 v149, v68, 0x3dd53b94, v140
	v_fmamk_f32 v150, v69, 0x3dd53b94, v140
	v_fmamk_f32 v151, v70, 0x3dd53b94, v140
	v_fmamk_f32 v152, v71, 0x3dd53b94, v140
	v_fmamk_f32 v153, v72, 0x3dd53b94, v140
	v_fmamk_f32 v154, v73, 0x3dd53b94, v140
	v_fmamk_f32 v155, v74, 0x3dd53b94, v140
	v_fmamk_f32 v156, v75, 0x3dd53b94, v140
	v_fmamk_f32 v157, v76, 0x3dd53b94, v140
	v_fmamk_f32 v158, v77, 0x3dd53b94, v140
	v_fmamk_f32 v159, v78, 0x3dd53b94, v140
	v_fmamk_f32 v160, v79, 0x3dd53b94, v140
	v_fmamk_f32 v161, v80, 0x3dd53b94, v140
	v_fmac_f32_e32 v140, 0x3dd53b94, v81
	s_waitcnt lgkmcnt(0)
	s_barrier
	v_cmp_lt_i32_e32 vcc, s17, v193
	v_mov_b32_e32 v66, 0xf149f2ca
	v_mov_b32_e32 v67, 0xf149f2ca
	v_mov_b32_e32 v68, 0xf149f2ca
	v_mov_b32_e32 v69, 0xf149f2ca
	v_mov_b32_e32 v70, 0xf149f2ca
	v_mov_b32_e32 v71, 0xf149f2ca
	v_mov_b32_e32 v72, 0xf149f2ca
	v_mov_b32_e32 v73, 0xf149f2ca
	v_mov_b32_e32 v74, 0xf149f2ca
	v_mov_b32_e32 v75, 0xf149f2ca
	v_mov_b32_e32 v76, 0xf149f2ca
	v_mov_b32_e32 v77, 0xf149f2ca
	v_mov_b32_e32 v78, 0xf149f2ca
	v_mov_b32_e32 v79, 0xf149f2ca
	v_mov_b32_e32 v80, 0xf149f2ca
	v_mov_b32_e32 v81, 0xf149f2ca
	v_mov_b32_e32 v82, 0xf149f2ca
	v_mov_b32_e32 v83, 0xf149f2ca
	v_mov_b32_e32 v84, 0xf149f2ca
	v_mov_b32_e32 v85, 0xf149f2ca
	v_mov_b32_e32 v86, 0xf149f2ca
	v_mov_b32_e32 v87, 0xf149f2ca
	v_mov_b32_e32 v88, 0xf149f2ca
	v_mov_b32_e32 v89, 0xf149f2ca
	v_mov_b32_e32 v90, 0xf149f2ca
	v_mov_b32_e32 v91, 0xf149f2ca
	v_mov_b32_e32 v92, 0xf149f2ca
	v_mov_b32_e32 v93, 0xf149f2ca
	v_mov_b32_e32 v94, 0xf149f2ca
	v_mov_b32_e32 v95, 0xf149f2ca
	v_mov_b32_e32 v96, 0xf149f2ca
	v_mov_b32_e32 v97, 0xf149f2ca
	s_and_saveexec_b64 s[12:13], vcc
	s_cbranch_execz .LBB0_711
	ds_read_b128 v[162:165], v185 offset:32768
	ds_read_b128 v[208:211], v185 offset:45056
	ds_read_b128 v[212:215], v186 offset:32768
	ds_read_b128 v[216:219], v186 offset:45056
	ds_read_b128 v[220:223], v188 offset:32768
	ds_read_b128 v[228:231], v188 offset:45056
	s_waitcnt lgkmcnt(5)
	v_mfma_f32_32x32x16_bf16 v[66:81], v[162:165], v[126:129], 0
	ds_read_b128 v[232:235], v187 offset:32768
	s_waitcnt lgkmcnt(5)
	v_mfma_f32_32x32x16_bf16 v[82:97], v[208:211], v[126:129], 0
	ds_read_b128 v[162:165], v187 offset:45056
	s_waitcnt lgkmcnt(5)
	v_mfma_f32_32x32x16_bf16 v[66:81], v[212:215], v[122:125], v[66:81]
	ds_read_b128 v[208:211], v185 offset:32896
	s_waitcnt lgkmcnt(5)
	v_mfma_f32_32x32x16_bf16 v[82:97], v[216:219], v[122:125], v[82:97]
	ds_read_b128 v[212:215], v185 offset:45184
	s_waitcnt lgkmcnt(5)
	v_mfma_f32_32x32x16_bf16 v[66:81], v[220:223], v[118:121], v[66:81]
	ds_read_b128 v[216:219], v186 offset:32896
	s_waitcnt lgkmcnt(5)
	v_mfma_f32_32x32x16_bf16 v[82:97], v[228:231], v[118:121], v[82:97]
	ds_read_b128 v[220:223], v186 offset:45184
	s_waitcnt lgkmcnt(5)
	v_mfma_f32_32x32x16_bf16 v[66:81], v[232:235], v[114:117], v[66:81]
	ds_read_b128 v[228:231], v188 offset:32896
	s_waitcnt lgkmcnt(5)
	v_mfma_f32_32x32x16_bf16 v[82:97], v[162:165], v[114:117], v[82:97]
	ds_read_b128 v[232:235], v188 offset:45184
	ds_read_b128 v[236:239], v183
	s_waitcnt lgkmcnt(6)
	v_mfma_f32_32x32x16_bf16 v[66:81], v[208:211], v[110:113], v[66:81]
	ds_read_b128 v[162:165], v187 offset:32896
	s_waitcnt lgkmcnt(6)
	v_mfma_f32_32x32x16_bf16 v[82:97], v[212:215], v[110:113], v[82:97]
	ds_read_b128 v[208:211], v187 offset:45184
	ds_read_b128 v[240:243], v183 offset:32
	s_waitcnt lgkmcnt(7)
	v_mfma_f32_32x32x16_bf16 v[66:81], v[216:219], v[106:109], v[66:81]
	ds_read_b128 v[212:215], v185 offset:33024
	s_waitcnt lgkmcnt(7)
	v_mfma_f32_32x32x16_bf16 v[82:97], v[220:223], v[106:109], v[82:97]
	ds_read_b128 v[216:219], v185 offset:45312
	ds_read_b128 v[244:247], v183 offset:64
	s_waitcnt lgkmcnt(8)
	v_mfma_f32_32x32x16_bf16 v[66:81], v[228:231], v[102:105], v[66:81]
	ds_read_b128 v[220:223], v186 offset:33024
	s_waitcnt lgkmcnt(8)
	v_mfma_f32_32x32x16_bf16 v[82:97], v[232:235], v[102:105], v[82:97]
	ds_read_b128 v[228:231], v186 offset:45312
	s_waitcnt lgkmcnt(7)
	v_mfma_f32_32x32x16_bf16 v[66:81], v[162:165], v[98:101], v[66:81]
	ds_read_b128 v[232:235], v188 offset:33024
	s_waitcnt lgkmcnt(7)
	v_mfma_f32_32x32x16_bf16 v[82:97], v[208:211], v[98:101], v[82:97]
	ds_read_b128 v[162:165], v188 offset:45312
	s_waitcnt lgkmcnt(6)
	v_mfma_f32_32x32x16_bf16 v[66:81], v[212:215], v[236:239], v[66:81]
	ds_read_b128 v[208:211], v187 offset:33024
	s_waitcnt lgkmcnt(6)
	v_mfma_f32_32x32x16_bf16 v[82:97], v[216:219], v[236:239], v[82:97]
	ds_read_b128 v[212:215], v187 offset:45312
	ds_read_b128 v[236:239], v183 offset:96
	s_waitcnt lgkmcnt(6)
	v_mfma_f32_32x32x16_bf16 v[66:81], v[220:223], v[240:243], v[66:81]
	s_waitcnt lgkmcnt(5)
	v_mfma_f32_32x32x16_bf16 v[82:97], v[228:231], v[240:243], v[82:97]
	s_waitcnt lgkmcnt(4)
	v_mfma_f32_32x32x16_bf16 v[66:81], v[232:235], v[244:247], v[66:81]
	s_waitcnt lgkmcnt(3)
	v_mfma_f32_32x32x16_bf16 v[82:97], v[162:165], v[244:247], v[82:97]
	s_waitcnt lgkmcnt(0)
	v_mfma_f32_32x32x16_bf16 v[66:81], v[208:211], v[236:239], v[66:81]
	s_waitcnt lgkmcnt(0)
	v_mfma_f32_32x32x16_bf16 v[82:97], v[212:215], v[236:239], v[82:97]

.LBB0_1405:
	s_cmp_lt_i32 s40, 14
	s_cselect_b64 s[8:9], -1, 0
	s_waitcnt lgkmcnt(0)
	s_and_b64 s[14:15], s[8:9], s[6:7]
	s_andn2_b64 vcc, exec, s[14:15]
	s_cbranch_vccnz .LBB0_1528
	s_mov_b32 s101, s2
	s_cmpk_lt_u32 s101, 0x800
	s_cbranch_scc0 .Lmy_sgu_done
	s_and_b32 s3, s42, 7
	s_cmp_lg_u32 s3, 0
	s_cbranch_scc1 .Lmy_sgu_done
	s_and_b32 s3, s2, 7
	v_readfirstlane_b32 s6, v226
	s_load_dwordx2 s[24:25], s[0:1], 0xc0
	s_load_dwordx2 s[26:27], s[0:1], 0xc8
	s_load_dwordx2 s[28:29], s[0:1], 0xd0
	s_lshr_b32 s6, s6, 6
	s_lshr_b32 s7, s6, 2
	s_and_b32 s6, s6, 3
	v_and_b32_e32 v1, 63, v226
	v_and_b32_e32 v2, 31, v1
	v_lshrrev_b32_e32 v3, 5, v1
	v_and_b32_e32 v4, 0x7f, v226
	v_lshlrev_b32_e32 v4, 2, v4
	s_lshl_b32 s8, s3, 7
	s_lshl_b32 s9, s7, 6
	s_add_i32 s8, s8, s9
	v_add_u32_e32 v5, s8, v2
	v_lshlrev_b32_e32 v14, 2, v5
	s_waitcnt lgkmcnt(0)
	global_load_dword v15, v14, s[24:25] offset:128
	global_load_dword v14, v14, s[24:25]
	s_lshl_b32 s9, s6, 5
	s_lshl_b32 s10, s3, 7
	s_add_i32 s10, s10, s9
	v_lshl_add_u32 v16, v3, 2, s10
	v_lshlrev_b32_e32 v16, 2, v16
	global_load_dword v31, v16, s[28:29] offset:108
	global_load_dword v30, v16, s[28:29] offset:104
	global_load_dword v29, v16, s[28:29] offset:100
	global_load_dword v28, v16, s[28:29] offset:96
	global_load_dword v27, v16, s[28:29] offset:76
	global_load_dword v26, v16, s[28:29] offset:72
	global_load_dword v25, v16, s[28:29] offset:68
	global_load_dword v24, v16, s[28:29] offset:64
	global_load_dword v23, v16, s[28:29] offset:44
	global_load_dword v22, v16, s[28:29] offset:40
	global_load_dword v21, v16, s[28:29] offset:36
	global_load_dword v20, v16, s[28:29] offset:32
	global_load_dword v19, v16, s[28:29] offset:12
	global_load_dword v18, v16, s[28:29] offset:8
	global_load_dword v17, v16, s[28:29] offset:4
	global_load_dword v16, v16, s[28:29]
	s_lshl_b32 s11, s3, 16
	s_lshl_b32 s12, s6, 14
	s_add_i32 s11, s11, s12
	v_lshlrev_b32_e32 v32, 9, v2
	v_lshl_add_u32 v32, v3, 5, v32
	v_add_u32_e32 v32, s11, v32
	global_load_dwordx4 v[92:95], v32, s[26:27] offset:464
	global_load_dwordx4 v[88:91], v32, s[26:27] offset:448
	global_load_dwordx4 v[84:87], v32, s[26:27] offset:400
	global_load_dwordx4 v[80:83], v32, s[26:27] offset:384
	global_load_dwordx4 v[76:79], v32, s[26:27] offset:336
	global_load_dwordx4 v[72:75], v32, s[26:27] offset:320
	global_load_dwordx4 v[68:71], v32, s[26:27] offset:272
	global_load_dwordx4 v[64:67], v32, s[26:27] offset:256
	global_load_dwordx4 v[60:63], v32, s[26:27] offset:208
	global_load_dwordx4 v[56:59], v32, s[26:27] offset:192
	global_load_dwordx4 v[52:55], v32, s[26:27] offset:144
	global_load_dwordx4 v[48:51], v32, s[26:27] offset:128
	global_load_dwordx4 v[44:47], v32, s[26:27] offset:80
	global_load_dwordx4 v[40:43], v32, s[26:27] offset:64
	global_load_dwordx4 v[36:39], v32, s[26:27] offset:16
	global_load_dwordx4 v[32:35], v32, s[26:27]
	v_mov_b32_e32 v6, 0x10600
	v_mul_u32_u24_e32 v5, v5, v6
	v_lshl_add_u32 v5, v3, 4, v5
	v_add_u32_e32 v6, 0x20c000, v5
	v_lshlrev_b32_e32 v7, 5, v3
	s_mul_i32 s12, s6, 0x4200
	s_lshl_b32 s13, s7, 8
	s_add_i32 s12, s12, s13
	s_addk_i32 s12, 0x400
	v_mul_u32_u24_e32 v8, 0x840, v3
	v_lshl_add_u32 v8, v2, 2, v8
	v_add_u32_e32 v8, s12, v8
	v_lshrrev_b32_e32 v9, 4, v226
	v_mul_u32_u24_e32 v9, 0x210, v9
	v_and_b32_e32 v10, 15, v226
	v_lshl_add_u32 v9, v10, 5, v9
	v_add_u32_e32 v9, 0x400, v9
	v_lshrrev_b32_e32 v11, 4, v226
	v_lshlrev_b32_e32 v11, 11, v11
	v_lshl_add_u32 v10, v10, 4, v11
	v_add_u32_e32 v11, 0x10000, v10
	v_add_u32_e32 v12, 0x20000, v10
	v_add_u32_e32 v13, 0x30000, v10
	s_waitcnt vmcnt(30)
